# rwkv2 role-2 beta: hand-written forward substitutions (streamed Mab reads, single fmac chain per row)
# speedup vs baseline: 1.1193x; 1.0399x over previous
; #define MFMA16(a, b, c) __builtin_amdgcn_mfma_f32_16x16x32_bf16((a), (b), (c), 0, 0, 0)
; #define TRI_ROW(dst, base, t) do { dst[0] = *(const f32x4*)(Mx + (base) + (t) * 16); dst[1] = *(const f32x4*)(Mx + (base) + (t) * 16 + 4); dst[2] = *(const f32x4*)(Mx + (base) + (t) * 16 + 8); dst[3] = *(const f32x4*)(Mx + (base) + (t) * 16 + 12); } while (0)
; #define TRI_NEXT(rc, rn) do { _Pragma("unroll") for (int i_ = 0; i_ < 4; ++i_) rc[i_] = rn[i_]; asm volatile("" ::: "memory"); } while (0)
; __device__ unsigned long long rwkv2_phase(const Params& p, unsigned char* smem) {
;     ...
;                     } else {
;                         float* Vh = (float*)(set2 + 4608);
;                         { const u16* VT = (const u16*)(S1b + (cm % 3) * 10560 + 8192);
;                           const bf16x8 makf = *(const bf16x8*)(Mxb + 1024 + l15 * 32 + 8 * lq);
; #pragma unroll
;                           for (int nt = 0; nt < 4; ++nt) { u32x4 vz = {0u, 0u, 0u, 0u}; if (lq < 2) vz = *(const u32x4*)(VT + (16 * nt + l15) * 16 + 8 * lq);
;                               const f32x4 d = MFMA16(makf, as_frag(vz), ((f32x4){0.f, 0.f, 0.f, 0.f}));
; #pragma unroll
;                               for (int r = 0; r < 4; ++r) MVs[(4 * lq + r) * 64 + 16 * nt + l15] = d[r]; }
;                           asm volatile("s_waitcnt lgkmcnt(0)" ::: "memory"); }
;                         float vh[16], x0[16];
; #pragma unroll
;                         for (int t = 0; t < 16; ++t) x0[t] = MVs[t * 64 + lane];
;                         f32x4 rc[4], rn[4];
;                         TRI_ROW(rc, 0, 0);
; #pragma unroll
;                         for (int t = 0; t < 16; ++t) { if (t < 15) TRI_ROW(rn, 0, t + 1);
;                             float pa[4] = {x0[t], 0.f, 0.f, 0.f};
; #pragma unroll
;                             for (int s = 0; s + 1 < t; ++s) pa[s & 3] += rc[s >> 2][s & 3] * vh[s];
;                             float acc = (pa[0] + pa[1]) + (pa[2] + pa[3]);
;                             if (t >= 1) acc += rc[(t - 1) >> 2][(t - 1) & 3] * vh[t - 1];
;                             vh[t] = acc; Vh[t * 64 + lane] = acc;
;                             TRI_NEXT(rc, rn); }
.LBB0_908:
	s_andn2_b64 vcc, exec, s[26:27]
	s_cbranch_vccnz .LBB0_922
	s_mul_i32 s26, s69, 0x4200
	s_add_i32 s28, s26, 0
	s_add_i32 s28, s28, 0x19d40
	s_mov_b64 s[26:27], -1
	s_and_b64 vcc, exec, s[60:61]
	s_cbranch_vccz .LBB0_919
	s_mul_hi_i32 s26, s68, 0x55555556
	s_lshr_b32 s27, s26, 31
	s_add_i32 s26, s26, s27
	v_lshlrev_b32_e32 v3, 6, v72
	v_lshlrev_b32_e32 v4, 4, v73
	v_readlane_b32 s16, v251, 63
	s_mul_i32 s26, s26, 3
	s_sub_i32 s26, s68, s26
	v_add3_u32 v3, s16, v3, v4
	ds_read_b128 v[42:45], v3
	s_mulk_i32 s26, 0x2940
	s_add_i32 s26, s26, 0
	s_add_i32 s26, s26, 0xe380
	v_lshlrev_b32_e32 v3, 5, v72
	v_cmp_gt_i32_e32 vcc, 2, v73
	v_add3_u32 v3, s26, v3, v4
	v_mov_b32_e32 v46, 0
	v_mov_b32_e32 v48, 0
	v_mov_b32_e32 v49, 0
	v_mov_b32_e32 v50, 0
	v_mov_b32_e32 v51, 0
	s_and_saveexec_b64 s[26:27], vcc
	ds_read_b128 v[48:51], v3 offset:8192
	s_or_b64 exec, exec, s[26:27]
	s_waitcnt lgkmcnt(0)
	v_mfma_f32_16x16x32_bf16 v[48:51], v[42:45], v[48:51], 0
	v_lshlrev_b32_e32 v4, 10, v73
	v_lshlrev_b32_e32 v5, 2, v72
	v_readlane_b32 s16, v250, 1
	v_mov_b32_e32 v47, 0
	s_nop 0
	v_add3_u32 v4, s16, v4, v5
	s_nop 1
	ds_write2st64_b32 v4, v48, v49 offset1:1
	ds_write2st64_b32 v4, v50, v51 offset0:2 offset1:3
	v_mov_b32_e32 v48, 0
	v_mov_b32_e32 v49, 0
	s_and_saveexec_b64 s[26:27], vcc
	ds_read_b128 v[46:49], v3 offset:8704
	s_or_b64 exec, exec, s[26:27]
	s_waitcnt lgkmcnt(0)
	v_mfma_f32_16x16x32_bf16 v[46:49], v[42:45], v[46:49], 0
	v_mov_b32_e32 v50, 0
	v_mov_b32_e32 v51, 0
	s_nop 5
	ds_write2_b32 v4, v46, v47 offset0:16 offset1:80
	ds_write2_b32 v4, v48, v49 offset0:144 offset1:208
	v_mov_b32_e32 v46, 0
	v_mov_b32_e32 v48, 0
	v_mov_b32_e32 v49, 0
	s_and_saveexec_b64 s[26:27], vcc
	ds_read_b128 v[48:51], v3 offset:9216
	s_or_b64 exec, exec, s[26:27]
	s_waitcnt lgkmcnt(0)
	v_mfma_f32_16x16x32_bf16 v[48:51], v[42:45], v[48:51], 0
	v_mov_b32_e32 v47, 0
	s_nop 6
	ds_write2_b32 v4, v48, v49 offset0:32 offset1:96
	ds_write2_b32 v4, v50, v51 offset0:160 offset1:224
	v_mov_b32_e32 v48, 0
	v_mov_b32_e32 v49, 0
	s_and_saveexec_b64 s[26:27], vcc
	ds_read_b128 v[46:49], v3 offset:9728
	s_or_b64 exec, exec, s[26:27]
	s_waitcnt lgkmcnt(0)
	v_mfma_f32_16x16x32_bf16 v[42:45], v[42:45], v[46:49], 0
	v_lshlrev_b32_e32 v3, 2, v74
	v_add_u32_e32 v5, 0, v3
	v_add_u32_e32 v75, s28, v3
	s_nop 4
	ds_write2_b32 v4, v42, v43 offset0:48 offset1:112
	ds_write2_b32 v4, v44, v45 offset0:176 offset1:240
	s_waitcnt lgkmcnt(0)
	v_add_u32_e32 v42, 0x18b40, v5
	ds_read_b32 v76, v42
	ds_read_b32 v77, v42 offset:256
	ds_read_b32 v78, v42 offset:512
	ds_read_b32 v79, v42 offset:768
	ds_read_b32 v80, v42 offset:1024
	ds_read_b32 v81, v42 offset:1280
	ds_read_b32 v82, v42 offset:1536
	ds_read_b32 v83, v42 offset:1792
	ds_read_b32 v84, v42 offset:2048
	ds_read_b32 v85, v42 offset:2304
	ds_read_b32 v86, v42 offset:2560
	ds_read_b32 v87, v42 offset:2816
	ds_read_b32 v88, v42 offset:3072
	ds_read_b32 v89, v42 offset:3328
	ds_read_b32 v90, v42 offset:3584
	ds_read_b32 v91, v42 offset:3840
	v_mov_b32_e32 v234, 0x15f40
	ds_read_b128 v[186:189], v234 offset:64
	ds_read_b128 v[190:193], v234 offset:128
	ds_read_b128 v[194:197], v234 offset:192
	ds_read_b128 v[198:201], v234 offset:256
	ds_read_b128 v[202:205], v234 offset:320
	ds_read_b128 v[206:209], v234 offset:336
	ds_read_b128 v[210:213], v234 offset:384
	ds_read_b128 v[214:217], v234 offset:400
	ds_read_b128 v[218:221], v234 offset:448
	ds_read_b128 v[222:225], v234 offset:464
	ds_read_b128 v[226:229], v234 offset:512
	ds_read_b128 v[230:233], v234 offset:528
	s_waitcnt lgkmcnt(12)
	s_waitcnt lgkmcnt(11)
	v_fmac_f32_e32 v77, v186, v76
	ds_read_b128 v[186:189], v234 offset:576
	s_waitcnt lgkmcnt(11)
	v_fmac_f32_e32 v78, v190, v76
	v_fmac_f32_e32 v78, v191, v77
	ds_read_b128 v[190:193], v234 offset:592
	s_waitcnt lgkmcnt(11)
	v_fmac_f32_e32 v79, v194, v76
	v_fmac_f32_e32 v79, v195, v77
	v_fmac_f32_e32 v79, v196, v78
	ds_read_b128 v[194:197], v234 offset:608
	s_waitcnt lgkmcnt(11)
	v_fmac_f32_e32 v80, v198, v76
	v_fmac_f32_e32 v80, v199, v77
	v_fmac_f32_e32 v80, v200, v78
	v_fmac_f32_e32 v80, v201, v79
	ds_read_b128 v[198:201], v234 offset:640
	s_waitcnt lgkmcnt(11)
	v_fmac_f32_e32 v81, v202, v76
	v_fmac_f32_e32 v81, v203, v77
	v_fmac_f32_e32 v81, v204, v78
	v_fmac_f32_e32 v81, v205, v79
	ds_read_b128 v[202:205], v234 offset:656
	s_waitcnt lgkmcnt(11)
	v_fmac_f32_e32 v81, v206, v80
	ds_read_b128 v[206:209], v234 offset:672
	s_waitcnt lgkmcnt(11)
	v_fmac_f32_e32 v82, v210, v76
	v_fmac_f32_e32 v82, v211, v77
	v_fmac_f32_e32 v82, v212, v78
	v_fmac_f32_e32 v82, v213, v79
	ds_read_b128 v[210:213], v234 offset:704
	s_waitcnt lgkmcnt(11)
	v_fmac_f32_e32 v82, v214, v80
	v_fmac_f32_e32 v82, v215, v81
	ds_read_b128 v[214:217], v234 offset:720
	s_waitcnt lgkmcnt(11)
	v_fmac_f32_e32 v83, v218, v76
	v_fmac_f32_e32 v83, v219, v77
	v_fmac_f32_e32 v83, v220, v78
	v_fmac_f32_e32 v83, v221, v79
	ds_read_b128 v[218:221], v234 offset:736
	s_waitcnt lgkmcnt(11)
	v_fmac_f32_e32 v83, v222, v80
	v_fmac_f32_e32 v83, v223, v81
	v_fmac_f32_e32 v83, v224, v82
	ds_read_b128 v[222:225], v234 offset:768
	s_waitcnt lgkmcnt(11)
	v_fmac_f32_e32 v84, v226, v76
	v_fmac_f32_e32 v84, v227, v77
	v_fmac_f32_e32 v84, v228, v78
	v_fmac_f32_e32 v84, v229, v79
	ds_read_b128 v[226:229], v234 offset:784
	s_waitcnt lgkmcnt(11)
	v_fmac_f32_e32 v84, v230, v80
	v_fmac_f32_e32 v84, v231, v81
	v_fmac_f32_e32 v84, v232, v82
	v_fmac_f32_e32 v84, v233, v83
	ds_read_b128 v[230:233], v234 offset:800
	s_waitcnt lgkmcnt(11)
	v_fmac_f32_e32 v85, v186, v76
	v_fmac_f32_e32 v85, v187, v77
	v_fmac_f32_e32 v85, v188, v78
	v_fmac_f32_e32 v85, v189, v79
	ds_read_b128 v[186:189], v234 offset:832
	s_waitcnt lgkmcnt(11)
; __device__ __forceinline__ unsigned pk2(float lo, float hi) { unsigned r; asm volatile("v_cvt_pk_bf16_f32 %0, %1, %2" : "=v"(r) : "v"(lo), "v"(hi)); return r; }
; #define TRI_ROW(dst, base, t) do { dst[0] = *(const f32x4*)(Mx + (base) + (t) * 16); dst[1] = *(const f32x4*)(Mx + (base) + (t) * 16 + 4); dst[2] = *(const f32x4*)(Mx + (base) + (t) * 16 + 8); dst[3] = *(const f32x4*)(Mx + (base) + (t) * 16 + 12); } while (0)
; #define TRI_NEXT(rc, rn) do { _Pragma("unroll") for (int i_ = 0; i_ < 4; ++i_) rc[i_] = rn[i_]; asm volatile("" ::: "memory"); } while (0)
; __device__ unsigned long long rwkv2_phase(const Params& p, unsigned char* smem) {
;     ...
;                         float vh[16], x0[16];
; #pragma unroll
;                         for (int t = 0; t < 16; ++t) x0[t] = MVs[t * 64 + lane];
;                         f32x4 rc[4], rn[4];
;                         TRI_ROW(rc, 0, 0);
; #pragma unroll
;                         for (int t = 0; t < 16; ++t) { if (t < 15) TRI_ROW(rn, 0, t + 1);
;                             float pa[4] = {x0[t], 0.f, 0.f, 0.f};
; #pragma unroll
;                             for (int s = 0; s + 1 < t; ++s) pa[s & 3] += rc[s >> 2][s & 3] * vh[s];
;                             float acc = (pa[0] + pa[1]) + (pa[2] + pa[3]);
;                             if (t >= 1) acc += rc[(t - 1) >> 2][(t - 1) & 3] * vh[t - 1];
;                             vh[t] = acc; Vh[t * 64 + lane] = acc;
;                             TRI_NEXT(rc, rn); }
;                         { u32x4 q0, q1; q0.x = pk2(vh[0], vh[1]); q0.y = pk2(vh[2], vh[3]); q0.z = pk2(vh[4], vh[5]); q0.w = pk2(vh[6], vh[7]);
;                           q1.x = pk2(vh[8], vh[9]); q1.y = pk2(vh[10], vh[11]); q1.z = pk2(vh[12], vh[13]); q1.w = pk2(vh[14], vh[15]);
;                           *(u32x4*)(VhT + lane * 16) = q0; *(u32x4*)(VhT + lane * 16 + 8) = q1; }
	v_fmac_f32_e32 v85, v190, v80
	v_fmac_f32_e32 v85, v191, v81
	v_fmac_f32_e32 v85, v192, v82
	v_fmac_f32_e32 v85, v193, v83
	ds_read_b128 v[190:193], v234 offset:848
	s_waitcnt lgkmcnt(11)
	v_fmac_f32_e32 v85, v194, v84
	ds_read_b128 v[194:197], v234 offset:864
	s_waitcnt lgkmcnt(11)
	v_fmac_f32_e32 v86, v198, v76
	v_fmac_f32_e32 v86, v199, v77
	v_fmac_f32_e32 v86, v200, v78
	v_fmac_f32_e32 v86, v201, v79
	ds_read_b128 v[198:201], v234 offset:880
	s_waitcnt lgkmcnt(11)
	v_fmac_f32_e32 v86, v202, v80
	v_fmac_f32_e32 v86, v203, v81
	v_fmac_f32_e32 v86, v204, v82
	v_fmac_f32_e32 v86, v205, v83
	ds_read_b128 v[202:205], v234 offset:896
	s_waitcnt lgkmcnt(11)
	v_fmac_f32_e32 v86, v206, v84
	v_fmac_f32_e32 v86, v207, v85
	ds_read_b128 v[206:209], v234 offset:912
	s_waitcnt lgkmcnt(11)
	v_fmac_f32_e32 v87, v210, v76
	v_fmac_f32_e32 v87, v211, v77
	v_fmac_f32_e32 v87, v212, v78
	v_fmac_f32_e32 v87, v213, v79
	ds_read_b128 v[210:213], v234 offset:928
	s_waitcnt lgkmcnt(11)
	v_fmac_f32_e32 v87, v214, v80
	v_fmac_f32_e32 v87, v215, v81
	v_fmac_f32_e32 v87, v216, v82
	v_fmac_f32_e32 v87, v217, v83
	ds_read_b128 v[214:217], v234 offset:944
	s_waitcnt lgkmcnt(11)
	v_fmac_f32_e32 v87, v218, v84
	v_fmac_f32_e32 v87, v219, v85
	v_fmac_f32_e32 v87, v220, v86
	ds_read_b128 v[218:221], v234 offset:960
	s_waitcnt lgkmcnt(11)
	v_fmac_f32_e32 v88, v222, v76
	v_fmac_f32_e32 v88, v223, v77
	v_fmac_f32_e32 v88, v224, v78
	v_fmac_f32_e32 v88, v225, v79
	ds_read_b128 v[222:225], v234 offset:976
	s_waitcnt lgkmcnt(11)
	v_fmac_f32_e32 v88, v226, v80
	v_fmac_f32_e32 v88, v227, v81
	v_fmac_f32_e32 v88, v228, v82
	v_fmac_f32_e32 v88, v229, v83
	ds_read_b128 v[226:229], v234 offset:992
	s_waitcnt lgkmcnt(11)
	v_fmac_f32_e32 v88, v230, v84
	v_fmac_f32_e32 v88, v231, v85
	v_fmac_f32_e32 v88, v232, v86
	v_fmac_f32_e32 v88, v233, v87
	ds_read_b128 v[230:233], v234 offset:1008
	s_waitcnt lgkmcnt(11)
	v_fmac_f32_e32 v89, v186, v76
	v_fmac_f32_e32 v89, v187, v77
	v_fmac_f32_e32 v89, v188, v78
	v_fmac_f32_e32 v89, v189, v79
	s_waitcnt lgkmcnt(10)
	v_fmac_f32_e32 v89, v190, v80
	v_fmac_f32_e32 v89, v191, v81
	v_fmac_f32_e32 v89, v192, v82
	v_fmac_f32_e32 v89, v193, v83
	s_waitcnt lgkmcnt(9)
	v_fmac_f32_e32 v89, v194, v84
	v_fmac_f32_e32 v89, v195, v85
	v_fmac_f32_e32 v89, v196, v86
	v_fmac_f32_e32 v89, v197, v87
	s_waitcnt lgkmcnt(8)
	v_fmac_f32_e32 v89, v198, v88
	s_waitcnt lgkmcnt(7)
	v_fmac_f32_e32 v90, v202, v76
	v_fmac_f32_e32 v90, v203, v77
	v_fmac_f32_e32 v90, v204, v78
	v_fmac_f32_e32 v90, v205, v79
	s_waitcnt lgkmcnt(6)
	v_fmac_f32_e32 v90, v206, v80
	v_fmac_f32_e32 v90, v207, v81
	v_fmac_f32_e32 v90, v208, v82
	v_fmac_f32_e32 v90, v209, v83
	s_waitcnt lgkmcnt(5)
	v_fmac_f32_e32 v90, v210, v84
	v_fmac_f32_e32 v90, v211, v85
	v_fmac_f32_e32 v90, v212, v86
	v_fmac_f32_e32 v90, v213, v87
	s_waitcnt lgkmcnt(4)
	v_fmac_f32_e32 v90, v214, v88
	v_fmac_f32_e32 v90, v215, v89
	s_waitcnt lgkmcnt(3)
	v_fmac_f32_e32 v91, v218, v76
	v_fmac_f32_e32 v91, v219, v77
	v_fmac_f32_e32 v91, v220, v78
	v_fmac_f32_e32 v91, v221, v79
	s_waitcnt lgkmcnt(2)
	v_fmac_f32_e32 v91, v222, v80
	v_fmac_f32_e32 v91, v223, v81
	v_fmac_f32_e32 v91, v224, v82
	v_fmac_f32_e32 v91, v225, v83
	s_waitcnt lgkmcnt(1)
	v_fmac_f32_e32 v91, v226, v84
	v_fmac_f32_e32 v91, v227, v85
	v_fmac_f32_e32 v91, v228, v86
	v_fmac_f32_e32 v91, v229, v87
	s_waitcnt lgkmcnt(0)
	v_fmac_f32_e32 v91, v230, v88
	v_fmac_f32_e32 v91, v231, v89
	v_fmac_f32_e32 v91, v232, v90
	ds_write_b32 v75, v76 offset:4608
	ds_write_b32 v75, v77 offset:4864
	ds_write_b32 v75, v78 offset:5120
	ds_write_b32 v75, v79 offset:5376
	ds_write_b32 v75, v80 offset:5632
	ds_write_b32 v75, v81 offset:5888
	ds_write_b32 v75, v82 offset:6144
	ds_write_b32 v75, v83 offset:6400
	ds_write_b32 v75, v84 offset:6656
	ds_write_b32 v75, v85 offset:6912
	ds_write_b32 v75, v86 offset:7168
	ds_write_b32 v75, v87 offset:7424
	ds_write_b32 v75, v88 offset:7680
	ds_write_b32 v75, v89 offset:7936
	ds_write_b32 v75, v90 offset:8192
	ds_write_b32 v75, v91 offset:8448
	v_cvt_pk_bf16_f32 v42, v76, v77
	v_cvt_pk_bf16_f32 v43, v78, v79
	v_cvt_pk_bf16_f32 v44, v80, v81
	v_cvt_pk_bf16_f32 v45, v82, v83
	v_cvt_pk_bf16_f32 v46, v84, v85
	v_cvt_pk_bf16_f32 v47, v86, v87
	v_cvt_pk_bf16_f32 v48, v88, v89
	v_cvt_pk_bf16_f32 v49, v90, v91
	s_mov_b64 s[26:27], 0
; __device__ __forceinline__ u16 f2bf(float f) { return (u16)(pk2(f, 0.f) & 0xffffu); }
; __device__ __forceinline__ float bf2f(u16 v) { return __uint_as_float(((unsigned)v) << 16); }
; #define TRI_ROW(dst, base, t) do { dst[0] = *(const f32x4*)(Mx + (base) + (t) * 16); dst[1] = *(const f32x4*)(Mx + (base) + (t) * 16 + 4); dst[2] = *(const f32x4*)(Mx + (base) + (t) * 16 + 8); dst[3] = *(const f32x4*)(Mx + (base) + (t) * 16 + 12); } while (0)
; #define TRI_NEXT(rc, rn) do { _Pragma("unroll") for (int i_ = 0; i_ < 4; ++i_) rc[i_] = rn[i_]; asm volatile("" ::: "memory"); } while (0)
; __device__ unsigned long long rwkv2_phase(const Params& p, unsigned char* smem) {
;     ...
;                     if (wave == 4) {
;                         u16* Ah = (u16*)set2;
;                         float ah[16], x0[16];
; #pragma unroll
;                         for (int t = 0; t < 16; ++t) x0[t] = bf2f(At[t * 72 + lane]);
;                         f32x4 rc[4], rn[4];
;                         TRI_ROW(rc, 0, 0);
; #pragma unroll
;                         for (int t = 0; t < 16; ++t) { if (t < 15) TRI_ROW(rn, 0, t + 1);
;                             float pa[4] = {x0[t], 0.f, 0.f, 0.f};
; #pragma unroll
;                             for (int s = 0; s + 1 < t; ++s) pa[s & 3] += rc[s >> 2][s & 3] * ah[s];
;                             float acc = (pa[0] + pa[1]) + (pa[2] + pa[3]);
;                             if (t >= 1) acc += rc[(t - 1) >> 2][(t - 1) & 3] * ah[t - 1];
;                             ah[t] = acc; Ah[t * 72 + lane] = f2bf(acc);
;                             TRI_NEXT(rc, rn); }
.LBB0_919:
	s_and_b64 vcc, exec, s[26:27]
	s_mov_b32 s26, s47
	s_cbranch_vccz .LBB0_921
	v_lshlrev_b32_e32 v4, 1, v74
	v_add_u32_e32 v5, s31, v4
	v_add_u32_e32 v75, s28, v4
	ds_read_u16 v76, v5 offset:39808
	ds_read_u16 v77, v5 offset:39952
	ds_read_u16 v78, v5 offset:40096
	ds_read_u16 v79, v5 offset:40240
	ds_read_u16 v80, v5 offset:40384
	ds_read_u16 v81, v5 offset:40528
	ds_read_u16 v82, v5 offset:40672
	ds_read_u16 v83, v5 offset:40816
	ds_read_u16 v84, v5 offset:40960
	ds_read_u16 v85, v5 offset:41104
	ds_read_u16 v86, v5 offset:41248
	ds_read_u16 v87, v5 offset:41392
	ds_read_u16 v88, v5 offset:41536
	ds_read_u16 v89, v5 offset:41680
	ds_read_u16 v90, v5 offset:41824
	ds_read_u16 v91, v5 offset:41968
	v_mov_b32_e32 v234, 0x15f40
	ds_read_b128 v[186:189], v234 offset:64
	ds_read_b128 v[190:193], v234 offset:128
	ds_read_b128 v[194:197], v234 offset:192
	ds_read_b128 v[198:201], v234 offset:256
	ds_read_b128 v[202:205], v234 offset:320
	ds_read_b128 v[206:209], v234 offset:336
	ds_read_b128 v[210:213], v234 offset:384
	ds_read_b128 v[214:217], v234 offset:400
	ds_read_b128 v[218:221], v234 offset:448
	ds_read_b128 v[222:225], v234 offset:464
	ds_read_b128 v[226:229], v234 offset:512
	ds_read_b128 v[230:233], v234 offset:528
	s_waitcnt lgkmcnt(12)
	v_lshlrev_b32_e32 v76, 16, v76
	v_lshlrev_b32_e32 v77, 16, v77
	v_lshlrev_b32_e32 v78, 16, v78
	v_lshlrev_b32_e32 v79, 16, v79
	v_lshlrev_b32_e32 v80, 16, v80
	v_lshlrev_b32_e32 v81, 16, v81
	v_lshlrev_b32_e32 v82, 16, v82
	v_lshlrev_b32_e32 v83, 16, v83
	v_lshlrev_b32_e32 v84, 16, v84
	v_lshlrev_b32_e32 v85, 16, v85
	v_lshlrev_b32_e32 v86, 16, v86
	v_lshlrev_b32_e32 v87, 16, v87
	v_lshlrev_b32_e32 v88, 16, v88
	v_lshlrev_b32_e32 v89, 16, v89
	v_lshlrev_b32_e32 v90, 16, v90
	v_lshlrev_b32_e32 v91, 16, v91
	s_waitcnt lgkmcnt(11)
	v_fmac_f32_e32 v77, v186, v76
	ds_read_b128 v[186:189], v234 offset:576
	s_waitcnt lgkmcnt(11)
	v_fmac_f32_e32 v78, v190, v76
	v_fmac_f32_e32 v78, v191, v77
	ds_read_b128 v[190:193], v234 offset:592
	s_waitcnt lgkmcnt(11)
	v_fmac_f32_e32 v79, v194, v76
	v_fmac_f32_e32 v79, v195, v77
	v_fmac_f32_e32 v79, v196, v78
	ds_read_b128 v[194:197], v234 offset:608
	s_waitcnt lgkmcnt(11)
	v_fmac_f32_e32 v80, v198, v76
	v_fmac_f32_e32 v80, v199, v77
	v_fmac_f32_e32 v80, v200, v78
	v_fmac_f32_e32 v80, v201, v79
	ds_read_b128 v[198:201], v234 offset:640
	s_waitcnt lgkmcnt(11)
	v_fmac_f32_e32 v81, v202, v76
	v_fmac_f32_e32 v81, v203, v77
	v_fmac_f32_e32 v81, v204, v78
	v_fmac_f32_e32 v81, v205, v79
	ds_read_b128 v[202:205], v234 offset:656
	s_waitcnt lgkmcnt(11)
	v_fmac_f32_e32 v81, v206, v80
	ds_read_b128 v[206:209], v234 offset:672
	s_waitcnt lgkmcnt(11)
	v_fmac_f32_e32 v82, v210, v76
	v_fmac_f32_e32 v82, v211, v77
	v_fmac_f32_e32 v82, v212, v78
	v_fmac_f32_e32 v82, v213, v79
	ds_read_b128 v[210:213], v234 offset:704
	s_waitcnt lgkmcnt(11)
	v_fmac_f32_e32 v82, v214, v80
	v_fmac_f32_e32 v82, v215, v81
	ds_read_b128 v[214:217], v234 offset:720
	s_waitcnt lgkmcnt(11)
	v_fmac_f32_e32 v83, v218, v76
	v_fmac_f32_e32 v83, v219, v77
	v_fmac_f32_e32 v83, v220, v78
	v_fmac_f32_e32 v83, v221, v79
	ds_read_b128 v[218:221], v234 offset:736
	s_waitcnt lgkmcnt(11)
	v_fmac_f32_e32 v83, v222, v80
	v_fmac_f32_e32 v83, v223, v81
	v_fmac_f32_e32 v83, v224, v82
	ds_read_b128 v[222:225], v234 offset:768
	s_waitcnt lgkmcnt(11)
	v_fmac_f32_e32 v84, v226, v76
	v_fmac_f32_e32 v84, v227, v77
	v_fmac_f32_e32 v84, v228, v78
	v_fmac_f32_e32 v84, v229, v79
	ds_read_b128 v[226:229], v234 offset:784
	s_waitcnt lgkmcnt(11)
	v_fmac_f32_e32 v84, v230, v80
	v_fmac_f32_e32 v84, v231, v81
	v_fmac_f32_e32 v84, v232, v82
	v_fmac_f32_e32 v84, v233, v83
	ds_read_b128 v[230:233], v234 offset:800
	s_waitcnt lgkmcnt(11)
	v_fmac_f32_e32 v85, v186, v76
	v_fmac_f32_e32 v85, v187, v77
	v_fmac_f32_e32 v85, v188, v78
	v_fmac_f32_e32 v85, v189, v79
	ds_read_b128 v[186:189], v234 offset:832
	s_waitcnt lgkmcnt(11)
	v_fmac_f32_e32 v85, v190, v80
	v_fmac_f32_e32 v85, v191, v81
	v_fmac_f32_e32 v85, v192, v82
	v_fmac_f32_e32 v85, v193, v83
	ds_read_b128 v[190:193], v234 offset:848
	s_waitcnt lgkmcnt(11)
; __device__ __forceinline__ unsigned pk2(float lo, float hi) { unsigned r; asm volatile("v_cvt_pk_bf16_f32 %0, %1, %2" : "=v"(r) : "v"(lo), "v"(hi)); return r; }
; __device__ __forceinline__ u16 f2bf(float f) { return (u16)(pk2(f, 0.f) & 0xffffu); }
; __device__ __forceinline__ float bf2f(u16 v) { return __uint_as_float(((unsigned)v) << 16); }
; #define TRI_ROW(dst, base, t) do { dst[0] = *(const f32x4*)(Mx + (base) + (t) * 16); dst[1] = *(const f32x4*)(Mx + (base) + (t) * 16 + 4); dst[2] = *(const f32x4*)(Mx + (base) + (t) * 16 + 8); dst[3] = *(const f32x4*)(Mx + (base) + (t) * 16 + 12); } while (0)
; #define TRI_NEXT(rc, rn) do { _Pragma("unroll") for (int i_ = 0; i_ < 4; ++i_) rc[i_] = rn[i_]; asm volatile("" ::: "memory"); } while (0)
; __device__ unsigned long long rwkv2_phase(const Params& p, unsigned char* smem) {
;     ...
;                     if (wave == 4) {
;                         u16* Ah = (u16*)set2;
;                         float ah[16], x0[16];
; #pragma unroll
;                         for (int t = 0; t < 16; ++t) x0[t] = bf2f(At[t * 72 + lane]);
;                         f32x4 rc[4], rn[4];
;                         TRI_ROW(rc, 0, 0);
; #pragma unroll
;                         for (int t = 0; t < 16; ++t) { if (t < 15) TRI_ROW(rn, 0, t + 1);
;                             float pa[4] = {x0[t], 0.f, 0.f, 0.f};
; #pragma unroll
;                             for (int s = 0; s + 1 < t; ++s) pa[s & 3] += rc[s >> 2][s & 3] * ah[s];
;                             float acc = (pa[0] + pa[1]) + (pa[2] + pa[3]);
;                             if (t >= 1) acc += rc[(t - 1) >> 2][(t - 1) & 3] * ah[t - 1];
;                             ah[t] = acc; Ah[t * 72 + lane] = f2bf(acc);
;                             TRI_NEXT(rc, rn); }
;                         { u32x4 q0, q1; q0.x = pk2(ah[0], ah[1]); q0.y = pk2(ah[2], ah[3]); q0.z = pk2(ah[4], ah[5]); q0.w = pk2(ah[6], ah[7]);
;                           q1.x = pk2(ah[8], ah[9]); q1.y = pk2(ah[10], ah[11]); q1.z = pk2(ah[12], ah[13]); q1.w = pk2(ah[14], ah[15]);
;                           *(u32x4*)(AhT + lane * 16) = q0; *(u32x4*)(AhT + lane * 16 + 8) = q1; }
	v_fmac_f32_e32 v85, v194, v84
	ds_read_b128 v[194:197], v234 offset:864
	s_waitcnt lgkmcnt(11)
	v_fmac_f32_e32 v86, v198, v76
	v_fmac_f32_e32 v86, v199, v77
	v_fmac_f32_e32 v86, v200, v78
	v_fmac_f32_e32 v86, v201, v79
	ds_read_b128 v[198:201], v234 offset:880
	s_waitcnt lgkmcnt(11)
	v_fmac_f32_e32 v86, v202, v80
	v_fmac_f32_e32 v86, v203, v81
	v_fmac_f32_e32 v86, v204, v82
	v_fmac_f32_e32 v86, v205, v83
	ds_read_b128 v[202:205], v234 offset:896
	s_waitcnt lgkmcnt(11)
	v_fmac_f32_e32 v86, v206, v84
	v_fmac_f32_e32 v86, v207, v85
	ds_read_b128 v[206:209], v234 offset:912
	s_waitcnt lgkmcnt(11)
	v_fmac_f32_e32 v87, v210, v76
	v_fmac_f32_e32 v87, v211, v77
	v_fmac_f32_e32 v87, v212, v78
	v_fmac_f32_e32 v87, v213, v79
	ds_read_b128 v[210:213], v234 offset:928
	s_waitcnt lgkmcnt(11)
	v_fmac_f32_e32 v87, v214, v80
	v_fmac_f32_e32 v87, v215, v81
	v_fmac_f32_e32 v87, v216, v82
	v_fmac_f32_e32 v87, v217, v83
	ds_read_b128 v[214:217], v234 offset:944
	s_waitcnt lgkmcnt(11)
	v_fmac_f32_e32 v87, v218, v84
	v_fmac_f32_e32 v87, v219, v85
	v_fmac_f32_e32 v87, v220, v86
	ds_read_b128 v[218:221], v234 offset:960
	s_waitcnt lgkmcnt(11)
	v_fmac_f32_e32 v88, v222, v76
	v_fmac_f32_e32 v88, v223, v77
	v_fmac_f32_e32 v88, v224, v78
	v_fmac_f32_e32 v88, v225, v79
	ds_read_b128 v[222:225], v234 offset:976
	s_waitcnt lgkmcnt(11)
	v_fmac_f32_e32 v88, v226, v80
	v_fmac_f32_e32 v88, v227, v81
	v_fmac_f32_e32 v88, v228, v82
	v_fmac_f32_e32 v88, v229, v83
	ds_read_b128 v[226:229], v234 offset:992
	s_waitcnt lgkmcnt(11)
	v_fmac_f32_e32 v88, v230, v84
	v_fmac_f32_e32 v88, v231, v85
	v_fmac_f32_e32 v88, v232, v86
	v_fmac_f32_e32 v88, v233, v87
	ds_read_b128 v[230:233], v234 offset:1008
	s_waitcnt lgkmcnt(11)
	v_fmac_f32_e32 v89, v186, v76
	v_fmac_f32_e32 v89, v187, v77
	v_fmac_f32_e32 v89, v188, v78
	v_fmac_f32_e32 v89, v189, v79
	s_waitcnt lgkmcnt(10)
	v_fmac_f32_e32 v89, v190, v80
	v_fmac_f32_e32 v89, v191, v81
	v_fmac_f32_e32 v89, v192, v82
	v_fmac_f32_e32 v89, v193, v83
	s_waitcnt lgkmcnt(9)
	v_fmac_f32_e32 v89, v194, v84
	v_fmac_f32_e32 v89, v195, v85
	v_fmac_f32_e32 v89, v196, v86
	v_fmac_f32_e32 v89, v197, v87
	s_waitcnt lgkmcnt(8)
	v_fmac_f32_e32 v89, v198, v88
	s_waitcnt lgkmcnt(7)
	v_fmac_f32_e32 v90, v202, v76
	v_fmac_f32_e32 v90, v203, v77
	v_fmac_f32_e32 v90, v204, v78
	v_fmac_f32_e32 v90, v205, v79
	s_waitcnt lgkmcnt(6)
	v_fmac_f32_e32 v90, v206, v80
	v_fmac_f32_e32 v90, v207, v81
	v_fmac_f32_e32 v90, v208, v82
	v_fmac_f32_e32 v90, v209, v83
	s_waitcnt lgkmcnt(5)
	v_fmac_f32_e32 v90, v210, v84
	v_fmac_f32_e32 v90, v211, v85
	v_fmac_f32_e32 v90, v212, v86
	v_fmac_f32_e32 v90, v213, v87
	s_waitcnt lgkmcnt(4)
	v_fmac_f32_e32 v90, v214, v88
	v_fmac_f32_e32 v90, v215, v89
	s_waitcnt lgkmcnt(3)
	v_fmac_f32_e32 v91, v218, v76
	v_fmac_f32_e32 v91, v219, v77
	v_fmac_f32_e32 v91, v220, v78
	v_fmac_f32_e32 v91, v221, v79
	s_waitcnt lgkmcnt(2)
	v_fmac_f32_e32 v91, v222, v80
	v_fmac_f32_e32 v91, v223, v81
	v_fmac_f32_e32 v91, v224, v82
	v_fmac_f32_e32 v91, v225, v83
	s_waitcnt lgkmcnt(1)
	v_fmac_f32_e32 v91, v226, v84
	v_fmac_f32_e32 v91, v227, v85
	v_fmac_f32_e32 v91, v228, v86
	v_fmac_f32_e32 v91, v229, v87
	s_waitcnt lgkmcnt(0)
	v_fmac_f32_e32 v91, v230, v88
	v_fmac_f32_e32 v91, v231, v89
	v_fmac_f32_e32 v91, v232, v90
	v_cvt_pk_bf16_f32 v42, v76, v77
	v_cvt_pk_bf16_f32 v43, v78, v79
	v_cvt_pk_bf16_f32 v44, v80, v81
	v_cvt_pk_bf16_f32 v45, v82, v83
	v_cvt_pk_bf16_f32 v46, v84, v85
	v_cvt_pk_bf16_f32 v47, v86, v87
	v_cvt_pk_bf16_f32 v48, v88, v89
	v_cvt_pk_bf16_f32 v49, v90, v91
	ds_write_b16 v75, v42
	ds_write_b16_d16_hi v75, v42 offset:144
	ds_write_b16 v75, v43 offset:288
	ds_write_b16_d16_hi v75, v43 offset:432
	ds_write_b16 v75, v44 offset:576
	ds_write_b16_d16_hi v75, v44 offset:720
	ds_write_b16 v75, v45 offset:864
	ds_write_b16_d16_hi v75, v45 offset:1008
	ds_write_b16 v75, v46 offset:1152
	ds_write_b16_d16_hi v75, v46 offset:1296
	ds_write_b16 v75, v47 offset:1440
	ds_write_b16_d16_hi v75, v47 offset:1584
	ds_write_b16 v75, v48 offset:1728
	ds_write_b16_d16_hi v75, v48 offset:1872
	ds_write_b16 v75, v49 offset:2016
	ds_write_b16_d16_hi v75, v49 offset:2160
	s_mov_b32 s26, s57
